# G1 epilogue: the 14 PROJ dwordx4 stores marked sc1 (agent-scope write-through) so the grid barrier's L2 writeback has less to flush
# speedup vs baseline: 1.0001x; 1.0001x over previous
; __device__ __forceinline__ u32x4 pack8(const f32x4& a, const f32x4& b) { u32x4 w; w.x = cvt_pk_bf16(a[0], a[1]); w.y = cvt_pk_bf16(a[2], a[3]); w.z = cvt_pk_bf16(b[0], b[1]); w.w = cvt_pk_bf16(b[2], b[3]); return w; }
;     __device__ __forceinline__ void apply(const Ld& d, int row, int c0, int, int, int, const f32x4& a0, const f32x4& b0, const f32x4& a1, const f32x4& b1) const { half(d.g0, row, c0, a0, b0); half(d.g1, row, c0 + 128, a1, b1); }
;     __device__ __forceinline__ void apply(const Ld& d, int row, int c0, int, int, int, const f32x4& a0, const f32x4& b0, const f32x4& a1, const f32x4& b1) const { half(d.g0, d.p0, row, c0, a0, b0); half(d.g1, d.p1, row, c0 + 128, a1, b1); }
;     __device__ __forceinline__ void apply(const Ld& d, int row, int c0, int pn, int wc, int fq, const f32x4& a0, const f32x4& b0, const f32x4& a1, const f32x4& b1) const {
;         const f32x4 t = (d.p[0] + d.p[1]) + (d.p[2] + d.p[3]);
;         const float inv = __builtin_amdgcn_rsqf(((t[0] + t[1]) + (t[2] + t[3])) * (1.f / DM) + EPS);
;         const f32x4 v0 = a0 * inv, v1 = b0 * inv, v2 = a1 * inv, v3 = b1 * inv;
;         if (pn < 18) { *(u32x4*)(proj + (size_t)row * PW + c0) = pack8(v0, v1); *(u32x4*)(proj + (size_t)row * PW + c0 + 128) = pack8(v2, v3); }
;         else if (c0 < 4608 + 32) *(u32x4*)(krope + (size_t)row * 32 + (c0 - 4608)) = pack8(v0, v1);
.LBB0_310:
	s_movk_i32 s44, 0xdc00
	v_ashrrev_i32_e32 v151, 31, v150
	v_pk_mul_f32 v[124:125], v[124:125], v[0:1] op_sel_hi:[1,0]
	v_pk_mul_f32 v[122:123], v[122:123], v[0:1] op_sel_hi:[1,0]
	v_pk_mul_f32 v[120:121], v[120:121], v[0:1] op_sel_hi:[1,0]
	v_pk_mul_f32 v[118:119], v[118:119], v[0:1] op_sel_hi:[1,0]
	s_mov_b32 s45, -1
	s_and_b64 vcc, exec, s[42:43]
	s_cbranch_vccz .LBB0_312
	v_mov_b64_e32 v[158:159], s[74:75]
	v_mad_i64_i32 v[160:161], s[42:43], v152, s29, v[158:159]
	v_cvt_pk_bf16_f32 v126, v130, v131
	v_cvt_pk_bf16_f32 v127, v132, v133
	v_cvt_pk_bf16_f32 v128, v156, v157
	v_cvt_pk_bf16_f32 v129, v154, v155
	v_lshl_add_u64 v[158:159], v[150:151], 1, v[160:161]
	s_mov_b64 s[44:45], 0x100
	s_or_b64 s[22:23], s[22:23], exec
	global_store_dwordx4 v[158:159], v[126:129], off sc1
	s_nop 1
	v_cvt_pk_bf16_f32 v126, v122, v123
	v_cvt_pk_bf16_f32 v127, v124, v125
	v_cvt_pk_bf16_f32 v128, v118, v119
	v_cvt_pk_bf16_f32 v129, v120, v121
.LBB0_312:
	s_and_saveexec_b64 s[42:43], s[22:23]
	s_cbranch_execz .LBB0_314
	v_lshl_add_u64 v[158:159], v[150:151], 1, v[160:161]
	v_lshl_add_u64 v[158:159], v[158:159], 0, s[44:45]
	global_store_dwordx4 v[158:159], v[126:129], off sc1

; __device__ __forceinline__ u32x4 pack8(const f32x4& a, const f32x4& b) { u32x4 w; w.x = cvt_pk_bf16(a[0], a[1]); w.y = cvt_pk_bf16(a[2], a[3]); w.z = cvt_pk_bf16(b[0], b[1]); w.w = cvt_pk_bf16(b[2], b[3]); return w; }
;     __device__ __forceinline__ void apply(const Ld& d, int row, int c0, int, int, int, const f32x4& a0, const f32x4& b0, const f32x4& a1, const f32x4& b1) const { half(d.g0, row, c0, a0, b0); half(d.g1, row, c0 + 128, a1, b1); }
;     __device__ __forceinline__ void apply(const Ld& d, int row, int c0, int, int, int, const f32x4& a0, const f32x4& b0, const f32x4& a1, const f32x4& b1) const { half(d.g0, d.p0, row, c0, a0, b0); half(d.g1, d.p1, row, c0 + 128, a1, b1); }
;     __device__ __forceinline__ void apply(const Ld& d, int row, int c0, int pn, int wc, int fq, const f32x4& a0, const f32x4& b0, const f32x4& a1, const f32x4& b1) const {
;         const f32x4 t = (d.p[0] + d.p[1]) + (d.p[2] + d.p[3]);
;         const float inv = __builtin_amdgcn_rsqf(((t[0] + t[1]) + (t[2] + t[3])) * (1.f / DM) + EPS);
;         const f32x4 v0 = a0 * inv, v1 = b0 * inv, v2 = a1 * inv, v3 = b1 * inv;
;         if (pn < 18) { *(u32x4*)(proj + (size_t)row * PW + c0) = pack8(v0, v1); *(u32x4*)(proj + (size_t)row * PW + c0 + 128) = pack8(v2, v3); }
;         else if (c0 < 4608 + 32) *(u32x4*)(krope + (size_t)row * 32 + (c0 - 4608)) = pack8(v0, v1);
.LBB0_327:
	s_movk_i32 s78, 0xdc00
	v_pk_mul_f32 v[108:109], v[108:109], v[0:1] op_sel_hi:[1,0]
	v_pk_mul_f32 v[106:107], v[106:107], v[0:1] op_sel_hi:[1,0]
	v_pk_mul_f32 v[104:105], v[104:105], v[0:1] op_sel_hi:[1,0]
	v_pk_mul_f32 v[102:103], v[102:103], v[0:1] op_sel_hi:[1,0]
	s_mov_b32 s79, -1
	s_and_b64 vcc, exec, s[44:45]
	s_cbranch_vccz .LBB0_329
	v_mov_b64_e32 v[124:125], s[74:75]
	v_mad_i64_i32 v[124:125], s[44:45], v118, s29, v[124:125]
	v_cvt_pk_bf16_f32 v110, v114, v115
	v_cvt_pk_bf16_f32 v111, v116, v117
	v_cvt_pk_bf16_f32 v112, v122, v123
	v_cvt_pk_bf16_f32 v113, v120, v121
	v_lshl_add_u64 v[126:127], v[150:151], 1, v[124:125]
	s_mov_b64 s[78:79], 0x100
	s_or_b64 s[0:1], s[0:1], exec
	global_store_dwordx4 v[126:127], v[110:113], off sc1
	s_nop 1
	v_cvt_pk_bf16_f32 v110, v106, v107
	v_cvt_pk_bf16_f32 v111, v108, v109
	v_cvt_pk_bf16_f32 v112, v102, v103
	v_cvt_pk_bf16_f32 v113, v104, v105
.LBB0_329:
	s_and_saveexec_b64 s[44:45], s[0:1]
	s_cbranch_execz .LBB0_331
	v_lshl_add_u64 v[124:125], v[150:151], 1, v[124:125]
	v_lshl_add_u64 v[124:125], v[124:125], 0, s[78:79]
	global_store_dwordx4 v[124:125], v[110:113], off sc1

; __device__ __forceinline__ u32x4 pack8(const f32x4& a, const f32x4& b) { u32x4 w; w.x = cvt_pk_bf16(a[0], a[1]); w.y = cvt_pk_bf16(a[2], a[3]); w.z = cvt_pk_bf16(b[0], b[1]); w.w = cvt_pk_bf16(b[2], b[3]); return w; }
;     __device__ __forceinline__ void apply(const Ld& d, int row, int c0, int, int, int, const f32x4& a0, const f32x4& b0, const f32x4& a1, const f32x4& b1) const { half(d.g0, row, c0, a0, b0); half(d.g1, row, c0 + 128, a1, b1); }
;     __device__ __forceinline__ void apply(const Ld& d, int row, int c0, int, int, int, const f32x4& a0, const f32x4& b0, const f32x4& a1, const f32x4& b1) const { half(d.g0, d.p0, row, c0, a0, b0); half(d.g1, d.p1, row, c0 + 128, a1, b1); }
;     __device__ __forceinline__ void apply(const Ld& d, int row, int c0, int pn, int wc, int fq, const f32x4& a0, const f32x4& b0, const f32x4& a1, const f32x4& b1) const {
;         const f32x4 t = (d.p[0] + d.p[1]) + (d.p[2] + d.p[3]);
;         const float inv = __builtin_amdgcn_rsqf(((t[0] + t[1]) + (t[2] + t[3])) * (1.f / DM) + EPS);
;         const f32x4 v0 = a0 * inv, v1 = b0 * inv, v2 = a1 * inv, v3 = b1 * inv;
;         if (pn < 18) { *(u32x4*)(proj + (size_t)row * PW + c0) = pack8(v0, v1); *(u32x4*)(proj + (size_t)row * PW + c0 + 128) = pack8(v2, v3); }
;         else if (c0 < 4608 + 32) *(u32x4*)(krope + (size_t)row * 32 + (c0 - 4608)) = pack8(v0, v1);
.LBB0_347:
	v_mov_b64_e32 v[124:125], s[74:75]
	v_mad_i64_i32 v[124:125], s[22:23], v118, s29, v[124:125]
	v_cvt_pk_bf16_f32 v94, v98, v99
	v_cvt_pk_bf16_f32 v95, v100, v101
	v_cvt_pk_bf16_f32 v96, v122, v123
	v_cvt_pk_bf16_f32 v97, v120, v121
	v_lshl_add_u64 v[126:127], v[150:151], 1, v[124:125]
	s_mov_b64 s[78:79], 0x100
	s_or_b64 s[0:1], s[0:1], exec
	global_store_dwordx4 v[126:127], v[94:97], off sc1
	s_nop 1
	v_cvt_pk_bf16_f32 v94, v90, v91
	v_cvt_pk_bf16_f32 v95, v92, v93
	v_cvt_pk_bf16_f32 v96, v86, v87
	v_cvt_pk_bf16_f32 v97, v88, v89
	s_and_saveexec_b64 s[22:23], s[0:1]
	s_cbranch_execz .LBB0_346
.LBB0_348:
	v_lshl_add_u64 v[124:125], v[150:151], 1, v[124:125]
	v_lshl_add_u64 v[124:125], v[124:125], 0, s[78:79]
	global_store_dwordx4 v[124:125], v[94:97], off sc1
	s_or_b64 exec, exec, s[22:23]
	s_and_b64 vcc, exec, s[44:45]
	s_cbranch_vccnz .LBB0_356

; __device__ __forceinline__ u32x4 pack8(const f32x4& a, const f32x4& b) { u32x4 w; w.x = cvt_pk_bf16(a[0], a[1]); w.y = cvt_pk_bf16(a[2], a[3]); w.z = cvt_pk_bf16(b[0], b[1]); w.w = cvt_pk_bf16(b[2], b[3]); return w; }
;     __device__ __forceinline__ void apply(const Ld& d, int row, int c0, int, int, int, const f32x4& a0, const f32x4& b0, const f32x4& a1, const f32x4& b1) const { half(d.g0, row, c0, a0, b0); half(d.g1, row, c0 + 128, a1, b1); }
;     __device__ __forceinline__ void apply(const Ld& d, int row, int c0, int, int, int, const f32x4& a0, const f32x4& b0, const f32x4& a1, const f32x4& b1) const { half(d.g0, d.p0, row, c0, a0, b0); half(d.g1, d.p1, row, c0 + 128, a1, b1); }
;     __device__ __forceinline__ void apply(const Ld& d, int row, int c0, int pn, int wc, int fq, const f32x4& a0, const f32x4& b0, const f32x4& a1, const f32x4& b1) const {
;         const f32x4 t = (d.p[0] + d.p[1]) + (d.p[2] + d.p[3]);
;         const float inv = __builtin_amdgcn_rsqf(((t[0] + t[1]) + (t[2] + t[3])) * (1.f / DM) + EPS);
;         const f32x4 v0 = a0 * inv, v1 = b0 * inv, v2 = a1 * inv, v3 = b1 * inv;
;         if (pn < 18) { *(u32x4*)(proj + (size_t)row * PW + c0) = pack8(v0, v1); *(u32x4*)(proj + (size_t)row * PW + c0 + 128) = pack8(v2, v3); }
;         else if (c0 < 4608 + 32) *(u32x4*)(krope + (size_t)row * 32 + (c0 - 4608)) = pack8(v0, v1);
.LBB0_364:
	v_mov_b64_e32 v[92:93], s[74:75]
	v_mad_i64_i32 v[92:93], s[22:23], v86, s29, v[92:93]
	v_cvt_pk_bf16_f32 v78, v82, v83
	v_cvt_pk_bf16_f32 v79, v84, v85
	v_cvt_pk_bf16_f32 v80, v90, v91
	v_cvt_pk_bf16_f32 v81, v88, v89
	v_lshl_add_u64 v[94:95], v[150:151], 1, v[92:93]
	s_mov_b64 s[78:79], 0x100
	s_or_b64 s[0:1], s[0:1], exec
	global_store_dwordx4 v[94:95], v[78:81], off sc1
	s_nop 1
	v_cvt_pk_bf16_f32 v78, v74, v75
	v_cvt_pk_bf16_f32 v79, v76, v77
	v_cvt_pk_bf16_f32 v80, v70, v71
	v_cvt_pk_bf16_f32 v81, v72, v73
	s_and_saveexec_b64 s[22:23], s[0:1]
	s_cbranch_execz .LBB0_363
.LBB0_365:
	v_lshl_add_u64 v[92:93], v[150:151], 1, v[92:93]
	v_lshl_add_u64 v[92:93], v[92:93], 0, s[78:79]
	global_store_dwordx4 v[92:93], v[78:81], off sc1
	s_or_b64 exec, exec, s[22:23]
	s_and_b64 vcc, exec, s[44:45]
	s_cbranch_vccnz .LBB0_373

; __device__ __forceinline__ u32x4 pack8(const f32x4& a, const f32x4& b) { u32x4 w; w.x = cvt_pk_bf16(a[0], a[1]); w.y = cvt_pk_bf16(a[2], a[3]); w.z = cvt_pk_bf16(b[0], b[1]); w.w = cvt_pk_bf16(b[2], b[3]); return w; }
;     __device__ __forceinline__ void apply(const Ld& d, int row, int c0, int, int, int, const f32x4& a0, const f32x4& b0, const f32x4& a1, const f32x4& b1) const { half(d.g0, row, c0, a0, b0); half(d.g1, row, c0 + 128, a1, b1); }
;     __device__ __forceinline__ void apply(const Ld& d, int row, int c0, int, int, int, const f32x4& a0, const f32x4& b0, const f32x4& a1, const f32x4& b1) const { half(d.g0, d.p0, row, c0, a0, b0); half(d.g1, d.p1, row, c0 + 128, a1, b1); }
;     __device__ __forceinline__ void apply(const Ld& d, int row, int c0, int pn, int wc, int fq, const f32x4& a0, const f32x4& b0, const f32x4& a1, const f32x4& b1) const {
;         const f32x4 t = (d.p[0] + d.p[1]) + (d.p[2] + d.p[3]);
;         const float inv = __builtin_amdgcn_rsqf(((t[0] + t[1]) + (t[2] + t[3])) * (1.f / DM) + EPS);
;         const f32x4 v0 = a0 * inv, v1 = b0 * inv, v2 = a1 * inv, v3 = b1 * inv;
;         if (pn < 18) { *(u32x4*)(proj + (size_t)row * PW + c0) = pack8(v0, v1); *(u32x4*)(proj + (size_t)row * PW + c0 + 128) = pack8(v2, v3); }
;         else if (c0 < 4608 + 32) *(u32x4*)(krope + (size_t)row * 32 + (c0 - 4608)) = pack8(v0, v1);
.LBB0_381:
	v_mov_b64_e32 v[94:95], s[74:75]
	v_mad_i64_i32 v[94:95], s[22:23], v86, s29, v[94:95]
	v_cvt_pk_bf16_f32 v62, v66, v67
	v_cvt_pk_bf16_f32 v63, v68, v69
	v_cvt_pk_bf16_f32 v64, v92, v93
	v_cvt_pk_bf16_f32 v65, v90, v91
	v_lshl_add_u64 v[96:97], v[150:151], 1, v[94:95]
	s_mov_b64 s[78:79], 0x100
	s_or_b64 s[0:1], s[0:1], exec
	global_store_dwordx4 v[96:97], v[62:65], off sc1
	s_nop 1
	v_cvt_pk_bf16_f32 v62, v58, v59
	v_cvt_pk_bf16_f32 v63, v60, v61
	v_cvt_pk_bf16_f32 v64, v54, v55
	v_cvt_pk_bf16_f32 v65, v56, v57
	s_and_saveexec_b64 s[22:23], s[0:1]
	s_cbranch_execz .LBB0_380
.LBB0_382:
	v_lshl_add_u64 v[94:95], v[150:151], 1, v[94:95]
	v_lshl_add_u64 v[94:95], v[94:95], 0, s[78:79]
	global_store_dwordx4 v[94:95], v[62:65], off sc1
	s_or_b64 exec, exec, s[22:23]
	s_and_b64 vcc, exec, s[44:45]
	s_cbranch_vccnz .LBB0_390

; __device__ __forceinline__ u32x4 pack8(const f32x4& a, const f32x4& b) { u32x4 w; w.x = cvt_pk_bf16(a[0], a[1]); w.y = cvt_pk_bf16(a[2], a[3]); w.z = cvt_pk_bf16(b[0], b[1]); w.w = cvt_pk_bf16(b[2], b[3]); return w; }
;     __device__ __forceinline__ void apply(const Ld& d, int row, int c0, int, int, int, const f32x4& a0, const f32x4& b0, const f32x4& a1, const f32x4& b1) const { half(d.g0, row, c0, a0, b0); half(d.g1, row, c0 + 128, a1, b1); }
;     __device__ __forceinline__ void apply(const Ld& d, int row, int c0, int, int, int, const f32x4& a0, const f32x4& b0, const f32x4& a1, const f32x4& b1) const { half(d.g0, d.p0, row, c0, a0, b0); half(d.g1, d.p1, row, c0 + 128, a1, b1); }
;     __device__ __forceinline__ void apply(const Ld& d, int row, int c0, int pn, int wc, int fq, const f32x4& a0, const f32x4& b0, const f32x4& a1, const f32x4& b1) const {
;         const f32x4 t = (d.p[0] + d.p[1]) + (d.p[2] + d.p[3]);
;         const float inv = __builtin_amdgcn_rsqf(((t[0] + t[1]) + (t[2] + t[3])) * (1.f / DM) + EPS);
;         const f32x4 v0 = a0 * inv, v1 = b0 * inv, v2 = a1 * inv, v3 = b1 * inv;
;         if (pn < 18) { *(u32x4*)(proj + (size_t)row * PW + c0) = pack8(v0, v1); *(u32x4*)(proj + (size_t)row * PW + c0 + 128) = pack8(v2, v3); }
;         else if (c0 < 4608 + 32) *(u32x4*)(krope + (size_t)row * 32 + (c0 - 4608)) = pack8(v0, v1);
.LBB0_398:
	v_mov_b64_e32 v[58:59], s[74:75]
	v_mad_i64_i32 v[58:59], s[22:23], v88, s29, v[58:59]
	v_cvt_pk_bf16_f32 v46, v50, v51
	v_cvt_pk_bf16_f32 v47, v52, v53
	v_cvt_pk_bf16_f32 v48, v56, v57
	v_cvt_pk_bf16_f32 v49, v54, v55
	v_lshl_add_u64 v[60:61], v[150:151], 1, v[58:59]
	s_mov_b64 s[78:79], 0x100
	s_or_b64 s[0:1], s[0:1], exec
	global_store_dwordx4 v[60:61], v[46:49], off sc1
	s_nop 1
	v_cvt_pk_bf16_f32 v46, v42, v43
	v_cvt_pk_bf16_f32 v47, v44, v45
	v_cvt_pk_bf16_f32 v48, v38, v39
	v_cvt_pk_bf16_f32 v49, v40, v41
	s_and_saveexec_b64 s[22:23], s[0:1]
	s_cbranch_execz .LBB0_397
.LBB0_399:
	v_lshl_add_u64 v[58:59], v[150:151], 1, v[58:59]
	v_lshl_add_u64 v[58:59], v[58:59], 0, s[78:79]
	global_store_dwordx4 v[58:59], v[46:49], off sc1
	s_or_b64 exec, exec, s[22:23]
	s_and_b64 vcc, exec, s[44:45]
	s_cbranch_vccnz .LBB0_407

; __device__ __forceinline__ u32x4 pack8(const f32x4& a, const f32x4& b) { u32x4 w; w.x = cvt_pk_bf16(a[0], a[1]); w.y = cvt_pk_bf16(a[2], a[3]); w.z = cvt_pk_bf16(b[0], b[1]); w.w = cvt_pk_bf16(b[2], b[3]); return w; }
;     __device__ __forceinline__ void apply(const Ld& d, int row, int c0, int, int, int, const f32x4& a0, const f32x4& b0, const f32x4& a1, const f32x4& b1) const { half(d.g0, row, c0, a0, b0); half(d.g1, row, c0 + 128, a1, b1); }
;     __device__ __forceinline__ void apply(const Ld& d, int row, int c0, int, int, int, const f32x4& a0, const f32x4& b0, const f32x4& a1, const f32x4& b1) const { half(d.g0, d.p0, row, c0, a0, b0); half(d.g1, d.p1, row, c0 + 128, a1, b1); }
;     __device__ __forceinline__ void apply(const Ld& d, int row, int c0, int pn, int wc, int fq, const f32x4& a0, const f32x4& b0, const f32x4& a1, const f32x4& b1) const {
;         const f32x4 t = (d.p[0] + d.p[1]) + (d.p[2] + d.p[3]);
;         const float inv = __builtin_amdgcn_rsqf(((t[0] + t[1]) + (t[2] + t[3])) * (1.f / DM) + EPS);
;         const f32x4 v0 = a0 * inv, v1 = b0 * inv, v2 = a1 * inv, v3 = b1 * inv;
;         if (pn < 18) { *(u32x4*)(proj + (size_t)row * PW + c0) = pack8(v0, v1); *(u32x4*)(proj + (size_t)row * PW + c0 + 128) = pack8(v2, v3); }
;         else if (c0 < 4608 + 32) *(u32x4*)(krope + (size_t)row * 32 + (c0 - 4608)) = pack8(v0, v1);
.LBB0_415:
	v_mov_b64_e32 v[60:61], s[74:75]
	v_mad_i64_i32 v[60:61], s[22:23], v54, s29, v[60:61]
	v_cvt_pk_bf16_f32 v30, v34, v35
	v_cvt_pk_bf16_f32 v31, v36, v37
	v_cvt_pk_bf16_f32 v32, v58, v59
	v_cvt_pk_bf16_f32 v33, v56, v57
	v_lshl_add_u64 v[62:63], v[150:151], 1, v[60:61]
	s_mov_b64 s[78:79], 0x100
	s_or_b64 s[0:1], s[0:1], exec
	global_store_dwordx4 v[62:63], v[30:33], off sc1
	s_nop 1
	v_cvt_pk_bf16_f32 v30, v26, v27
	v_cvt_pk_bf16_f32 v31, v28, v29
	v_cvt_pk_bf16_f32 v32, v22, v23
	v_cvt_pk_bf16_f32 v33, v24, v25
	s_and_saveexec_b64 s[22:23], s[0:1]
	s_cbranch_execz .LBB0_414
.LBB0_416:
	v_lshl_add_u64 v[60:61], v[150:151], 1, v[60:61]
	v_lshl_add_u64 v[60:61], v[60:61], 0, s[78:79]
	global_store_dwordx4 v[60:61], v[30:33], off sc1
	s_or_b64 exec, exec, s[22:23]
	s_and_b64 vcc, exec, s[44:45]
	s_cbranch_vccnz .LBB0_424
